# NSA pass 2: lane^1 / lane^2 importance reductions via DPP quad_perm moves instead of ds_bpermute with rebuilt addresses
# speedup vs baseline: 1.0105x; 1.0086x over previous
.LBB0_1576:
	v_add_u32_e32 v14, s0, v11
	v_add_u32_e32 v15, v14, v0
	ds_read_b128 v[80:83], v15
	ds_read_b128 v[84:87], v15 offset:32
	v_add_u32_e32 v14, 0xfffffe00, v13
	v_cmp_le_i32_e64 s[0:1], v14, v188
	s_waitcnt lgkmcnt(1)
	v_mfma_f32_32x32x16_bf16 v[64:79], v[80:83], v[144:147], v[48:63]
	ds_read_b128 v[80:83], v15 offset:64
	s_waitcnt lgkmcnt(1)
	v_mfma_f32_32x32x16_bf16 v[64:79], v[84:87], v[148:151], v[64:79]
	s_waitcnt lgkmcnt(0)
	v_mfma_f32_32x32x16_bf16 v[64:79], v[80:83], v[152:155], v[64:79]
	ds_read_b128 v[80:83], v15 offset:96
	s_waitcnt lgkmcnt(0)
	v_mfma_f32_32x32x16_bf16 v[64:79], v[80:83], v[156:159], v[64:79]
	s_nop 11
	v_exp_f32_e32 v64, v64
	v_exp_f32_e32 v65, v65
	v_exp_f32_e32 v66, v66
	v_exp_f32_e32 v67, v67
	v_mul_f32_e32 v64, v190, v64
	v_cndmask_b32_e64 v14, 0, v64, s[0:1]
	v_add_u32_e32 v64, 0xfffffe10, v13
	v_mul_f32_e32 v65, v190, v65
	v_cmp_le_i32_e64 s[0:1], v64, v188
	v_mul_f32_e32 v66, v190, v66
	v_mul_f32_e32 v67, v190, v67
	v_cndmask_b32_e64 v64, 0, v65, s[0:1]
	v_add_u32_e32 v65, 0xfffffe20, v13
	v_cmp_le_i32_e64 s[0:1], v65, v188
	v_add_f32_e32 v14, v14, v64
	s_nop 0
	v_cndmask_b32_e64 v65, 0, v66, s[0:1]
	v_add_u32_e32 v66, 0xfffffe30, v13
	v_cmp_le_i32_e64 s[0:1], v66, v188
	s_nop 1
	v_cndmask_b32_e64 v66, 0, v67, s[0:1]
	v_add_f32_e32 v64, v65, v66
	v_add_f32_e32 v14, v14, v64
	s_nop 0
	s_nop 1
	v_mov_b32_dpp v64, v14 quad_perm:[1,0,3,2] row_mask:0xf bank_mask:0xf
	s_waitcnt lgkmcnt(0)
	v_add_f32_e32 v64, v14, v64
	s_nop 0
	s_nop 1
	v_mov_b32_dpp v65, v64 quad_perm:[2,3,0,1] row_mask:0xf bank_mask:0xf
	s_nop 0
	s_nop 1
	v_mov_b32_dpp v14, v66 quad_perm:[1,0,3,2] row_mask:0xf bank_mask:0xf
	s_waitcnt lgkmcnt(0)
	v_add_f32_e32 v66, v66, v14
	s_nop 0
	s_nop 1
	v_mov_b32_dpp v67, v66 quad_perm:[2,3,0,1] row_mask:0xf bank_mask:0xf
	v_add_u32_e32 v14, s4, v191
	s_and_saveexec_b64 s[2:3], vcc
	s_cbranch_execz .LBB0_1581
	s_cmpk_gt_u32 s4, 0x7f
	s_cbranch_scc1 .LBB0_1579
	v_add_f32_e32 v64, v64, v65
	ds_add_f32 v12, v64

.LBB0_1581:
	s_or_b64 exec, exec, s[2:3]
	v_exp_f32_e32 v64, v68
	v_exp_f32_e32 v66, v69
	v_add_u32_e32 v65, 0xfffffe80, v13
	s_waitcnt lgkmcnt(0)
	v_exp_f32_e32 v67, v70
	v_mul_f32_e32 v64, v190, v64
	v_cmp_le_i32_e64 s[0:1], v65, v188
	v_add_u32_e32 v65, 0xfffffe90, v13
	v_mul_f32_e32 v66, v190, v66
	v_cndmask_b32_e64 v64, 0, v64, s[0:1]
	v_cmp_le_i32_e64 s[0:1], v65, v188
	v_exp_f32_e32 v68, v71
	v_mul_f32_e32 v67, v190, v67
	v_cndmask_b32_e64 v65, 0, v66, s[0:1]
	v_add_u32_e32 v66, 0xfffffea0, v13
	v_cmp_le_i32_e64 s[0:1], v66, v188
	v_mul_f32_e32 v68, v190, v68
	v_add_f32_e32 v64, v64, v65
	v_cndmask_b32_e64 v66, 0, v67, s[0:1]
	v_add_u32_e32 v67, 0xfffffeb0, v13
	v_cmp_le_i32_e64 s[0:1], v67, v188
	s_nop 1
	v_cndmask_b32_e64 v68, 0, v68, s[0:1]
	v_add_f32_e32 v65, v66, v68
	v_add_f32_e32 v64, v64, v65
	s_nop 1
	v_mov_b32_dpp v65, v64 quad_perm:[1,0,3,2] row_mask:0xf bank_mask:0xf
	s_waitcnt lgkmcnt(0)
	v_add_f32_e32 v64, v64, v65
	s_nop 0
	s_nop 1
	v_mov_b32_dpp v66, v68 quad_perm:[1,0,3,2] row_mask:0xf bank_mask:0xf
	s_nop 1
	v_mov_b32_dpp v67, v64 quad_perm:[2,3,0,1] row_mask:0xf bank_mask:0xf
	s_waitcnt lgkmcnt(0)
	v_add_f32_e32 v65, v68, v66
	s_nop 0
	s_nop 1
	v_mov_b32_dpp v66, v65 quad_perm:[2,3,0,1] row_mask:0xf bank_mask:0xf
	s_and_saveexec_b64 s[2:3], vcc
	s_cbranch_execz .LBB0_1586
	s_cmpk_gt_u32 s4, 0x7f
	s_cbranch_scc1 .LBB0_1584
	s_waitcnt lgkmcnt(0)
	v_add_f32_e32 v64, v64, v67
	ds_add_f32 v12, v64 offset:8

.LBB0_1586:
	s_or_b64 exec, exec, s[2:3]
	v_exp_f32_e32 v64, v72
	s_waitcnt lgkmcnt(0)
	v_exp_f32_e32 v66, v73
	v_add_u32_e32 v65, 0xffffff00, v13
	v_exp_f32_e32 v67, v74
	v_mul_f32_e32 v64, v190, v64
	v_cmp_le_i32_e64 s[0:1], v65, v188
	v_add_u32_e32 v65, 0xffffff10, v13
	v_mul_f32_e32 v66, v190, v66
	v_cndmask_b32_e64 v64, 0, v64, s[0:1]
	v_cmp_le_i32_e64 s[0:1], v65, v188
	v_exp_f32_e32 v68, v75
	v_mul_f32_e32 v67, v190, v67
	v_cndmask_b32_e64 v65, 0, v66, s[0:1]
	v_add_u32_e32 v66, 0xffffff20, v13
	v_cmp_le_i32_e64 s[0:1], v66, v188
	v_mul_f32_e32 v68, v190, v68
	v_add_f32_e32 v64, v64, v65
	v_cndmask_b32_e64 v66, 0, v67, s[0:1]
	v_add_u32_e32 v67, 0xffffff30, v13
	v_cmp_le_i32_e64 s[0:1], v67, v188
	s_nop 1
	v_cndmask_b32_e64 v68, 0, v68, s[0:1]
	v_add_f32_e32 v65, v66, v68
	v_add_f32_e32 v64, v64, v65
	s_nop 1
	v_mov_b32_dpp v65, v64 quad_perm:[1,0,3,2] row_mask:0xf bank_mask:0xf
	s_waitcnt lgkmcnt(0)
	v_add_f32_e32 v64, v64, v65
	s_nop 0
	s_nop 1
	v_mov_b32_dpp v66, v68 quad_perm:[1,0,3,2] row_mask:0xf bank_mask:0xf
	s_nop 1
	v_mov_b32_dpp v67, v64 quad_perm:[2,3,0,1] row_mask:0xf bank_mask:0xf
	s_waitcnt lgkmcnt(0)
	v_add_f32_e32 v65, v68, v66
	s_nop 0
	s_nop 1
	v_mov_b32_dpp v66, v65 quad_perm:[2,3,0,1] row_mask:0xf bank_mask:0xf
	s_and_saveexec_b64 s[2:3], vcc
	s_cbranch_execz .LBB0_1591
	s_cmpk_gt_u32 s4, 0x7f
	s_cbranch_scc1 .LBB0_1589
	s_waitcnt lgkmcnt(0)
	v_add_f32_e32 v64, v64, v67
	ds_add_f32 v12, v64 offset:16

.LBB0_1591:
	s_or_b64 exec, exec, s[2:3]
	v_exp_f32_e32 v64, v76
	s_waitcnt lgkmcnt(0)
	v_exp_f32_e32 v66, v77
	v_add_u32_e32 v65, 0xffffff80, v13
	v_exp_f32_e32 v67, v78
	v_mul_f32_e32 v64, v190, v64
	v_cmp_le_i32_e64 s[0:1], v65, v188
	v_add_u32_e32 v65, 0xffffff90, v13
	v_mul_f32_e32 v66, v190, v66
	v_cndmask_b32_e64 v64, 0, v64, s[0:1]
	v_cmp_le_i32_e64 s[0:1], v65, v188
	v_exp_f32_e32 v68, v79
	v_mul_f32_e32 v67, v190, v67
	v_cndmask_b32_e64 v65, 0, v66, s[0:1]
	v_add_u32_e32 v66, 0xffffffa0, v13
	v_cmp_le_i32_e64 s[0:1], v66, v188
	v_mul_f32_e32 v68, v190, v68
	v_add_f32_e32 v64, v64, v65
	v_cndmask_b32_e64 v66, 0, v67, s[0:1]
	v_add_u32_e32 v67, 0xffffffb0, v13
	v_cmp_le_i32_e64 s[0:1], v67, v188
	s_nop 1
	v_cndmask_b32_e64 v68, 0, v68, s[0:1]
	v_add_f32_e32 v65, v66, v68
	v_add_f32_e32 v64, v64, v65
	s_nop 1
	v_mov_b32_dpp v65, v64 quad_perm:[1,0,3,2] row_mask:0xf bank_mask:0xf
	s_waitcnt lgkmcnt(0)
	v_add_f32_e32 v64, v64, v65
	s_nop 0
	s_nop 1
	v_mov_b32_dpp v66, v68 quad_perm:[1,0,3,2] row_mask:0xf bank_mask:0xf
	s_nop 1
	v_mov_b32_dpp v67, v64 quad_perm:[2,3,0,1] row_mask:0xf bank_mask:0xf
	s_waitcnt lgkmcnt(0)
	v_add_f32_e32 v65, v68, v66
	s_nop 0
	s_nop 1
	v_mov_b32_dpp v66, v65 quad_perm:[2,3,0,1] row_mask:0xf bank_mask:0xf
	s_and_saveexec_b64 s[2:3], vcc
	s_cbranch_execz .LBB0_1596
	s_cmpk_gt_u32 s4, 0x7f
	s_cbranch_scc1 .LBB0_1594
	s_waitcnt lgkmcnt(0)
	v_add_f32_e32 v64, v64, v67
	ds_add_f32 v12, v64 offset:24

.LBB0_1596:
	s_or_b64 exec, exec, s[2:3]
	ds_read_b128 v[80:83], v15 offset:4608
	ds_read_b128 v[84:87], v15 offset:4640
	v_cmp_le_i32_e64 s[0:1], v13, v188
	s_waitcnt lgkmcnt(1)
	v_mfma_f32_32x32x16_bf16 v[64:79], v[80:83], v[144:147], v[48:63]
	ds_read_b128 v[80:83], v15 offset:4672
	s_waitcnt lgkmcnt(1)
	v_mfma_f32_32x32x16_bf16 v[64:79], v[84:87], v[148:151], v[64:79]
	s_waitcnt lgkmcnt(0)
	v_mfma_f32_32x32x16_bf16 v[64:79], v[80:83], v[152:155], v[64:79]
	ds_read_b128 v[80:83], v15 offset:4704
	s_waitcnt lgkmcnt(0)
	v_mfma_f32_32x32x16_bf16 v[64:79], v[80:83], v[156:159], v[64:79]
	s_nop 11
	v_exp_f32_e32 v15, v64
	v_exp_f32_e32 v65, v65
	v_exp_f32_e32 v66, v66
	v_add_u32_e32 v64, 16, v13
	v_mul_f32_e32 v15, v190, v15
	v_cndmask_b32_e64 v15, 0, v15, s[0:1]
	v_mul_f32_e32 v65, v190, v65
	v_cmp_le_i32_e64 s[0:1], v64, v188
	v_exp_f32_e32 v67, v67
	v_mul_f32_e32 v66, v190, v66
	v_cndmask_b32_e64 v64, 0, v65, s[0:1]
	v_add_u32_e32 v65, 32, v13
	v_cmp_le_i32_e64 s[0:1], v65, v188
	v_mul_f32_e32 v67, v190, v67
	v_add_f32_e32 v15, v15, v64
	v_cndmask_b32_e64 v65, 0, v66, s[0:1]
	v_add_u32_e32 v66, 48, v13
	v_cmp_le_i32_e64 s[0:1], v66, v188
	s_nop 1
	v_cndmask_b32_e64 v66, 0, v67, s[0:1]
	v_add_f32_e32 v64, v65, v66
	v_add_f32_e32 v15, v15, v64
	s_nop 1
	v_mov_b32_dpp v64, v15 quad_perm:[1,0,3,2] row_mask:0xf bank_mask:0xf
	s_waitcnt lgkmcnt(0)
	v_add_f32_e32 v15, v15, v64
	s_nop 0
	s_nop 1
	v_mov_b32_dpp v65, v66 quad_perm:[1,0,3,2] row_mask:0xf bank_mask:0xf
	s_waitcnt lgkmcnt(0)
	v_add_f32_e32 v65, v66, v65
	s_nop 1
	v_mov_b32_dpp v64, v15 quad_perm:[2,3,0,1] row_mask:0xf bank_mask:0xf
	s_nop 1
	v_mov_b32_dpp v66, v65 quad_perm:[2,3,0,1] row_mask:0xf bank_mask:0xf
	s_and_saveexec_b64 s[2:3], vcc
	s_cbranch_execz .LBB0_1601
	s_cmpk_gt_u32 s4, 0x7f
	s_cbranch_scc1 .LBB0_1599
	s_waitcnt lgkmcnt(0)
	v_add_f32_e32 v15, v15, v64
	ds_add_f32 v12, v15 offset:32

.LBB0_1601:
	s_or_b64 exec, exec, s[2:3]
	v_exp_f32_e32 v15, v68
	v_exp_f32_e32 v65, v69
	s_waitcnt lgkmcnt(0)
	v_add_u32_e32 v64, 0x80, v13
	s_waitcnt lgkmcnt(0)
	v_exp_f32_e32 v66, v70
	v_mul_f32_e32 v15, v190, v15
	v_cmp_le_i32_e64 s[0:1], v64, v188
	v_add_u32_e32 v64, 0x90, v13
	v_mul_f32_e32 v65, v190, v65
	v_cndmask_b32_e64 v15, 0, v15, s[0:1]
	v_cmp_le_i32_e64 s[0:1], v64, v188
	v_exp_f32_e32 v67, v71
	v_mul_f32_e32 v66, v190, v66
	v_cndmask_b32_e64 v64, 0, v65, s[0:1]
	v_add_u32_e32 v65, 0xa0, v13
	v_cmp_le_i32_e64 s[0:1], v65, v188
	v_mul_f32_e32 v67, v190, v67
	v_add_f32_e32 v15, v15, v64
	v_cndmask_b32_e64 v65, 0, v66, s[0:1]
	v_add_u32_e32 v66, 0xb0, v13
	v_cmp_le_i32_e64 s[0:1], v66, v188
	s_nop 1
	v_cndmask_b32_e64 v67, 0, v67, s[0:1]
	v_add_f32_e32 v64, v65, v67
	v_add_f32_e32 v15, v15, v64
	s_nop 1
	v_mov_b32_dpp v64, v15 quad_perm:[1,0,3,2] row_mask:0xf bank_mask:0xf
	s_waitcnt lgkmcnt(0)
	v_add_f32_e32 v15, v15, v64
	s_nop 0
	s_nop 1
	v_mov_b32_dpp v65, v67 quad_perm:[1,0,3,2] row_mask:0xf bank_mask:0xf
	s_nop 1
	v_mov_b32_dpp v66, v15 quad_perm:[2,3,0,1] row_mask:0xf bank_mask:0xf
	s_waitcnt lgkmcnt(0)
	v_add_f32_e32 v64, v67, v65
	s_nop 0
	s_nop 1
	v_mov_b32_dpp v65, v64 quad_perm:[2,3,0,1] row_mask:0xf bank_mask:0xf
	s_and_saveexec_b64 s[2:3], vcc
	s_cbranch_execz .LBB0_1606
	s_cmpk_gt_u32 s4, 0x7f
	s_cbranch_scc1 .LBB0_1604
	s_waitcnt lgkmcnt(0)
	v_add_f32_e32 v15, v15, v66
	ds_add_f32 v12, v15 offset:40

.LBB0_1606:
	s_or_b64 exec, exec, s[2:3]
	v_exp_f32_e32 v15, v72
	s_waitcnt lgkmcnt(0)
	v_exp_f32_e32 v65, v73
	v_add_u32_e32 v64, 0x100, v13
	v_exp_f32_e32 v66, v74
	v_mul_f32_e32 v15, v190, v15
	v_cmp_le_i32_e64 s[0:1], v64, v188
	v_add_u32_e32 v64, 0x110, v13
	v_mul_f32_e32 v65, v190, v65
	v_cndmask_b32_e64 v15, 0, v15, s[0:1]
	v_cmp_le_i32_e64 s[0:1], v64, v188
	v_exp_f32_e32 v67, v75
	v_mul_f32_e32 v66, v190, v66
	v_cndmask_b32_e64 v64, 0, v65, s[0:1]
	v_add_u32_e32 v65, 0x120, v13
	v_cmp_le_i32_e64 s[0:1], v65, v188
	v_mul_f32_e32 v67, v190, v67
	v_add_f32_e32 v15, v15, v64
	v_cndmask_b32_e64 v65, 0, v66, s[0:1]
	v_add_u32_e32 v66, 0x130, v13
	v_cmp_le_i32_e64 s[0:1], v66, v188
	s_nop 1
	v_cndmask_b32_e64 v67, 0, v67, s[0:1]
	v_add_f32_e32 v64, v65, v67
	v_add_f32_e32 v15, v15, v64
	s_nop 1
	v_mov_b32_dpp v64, v15 quad_perm:[1,0,3,2] row_mask:0xf bank_mask:0xf
	s_waitcnt lgkmcnt(0)
	v_add_f32_e32 v15, v15, v64
	s_nop 0
	s_nop 1
	v_mov_b32_dpp v65, v67 quad_perm:[1,0,3,2] row_mask:0xf bank_mask:0xf
	s_nop 1
	v_mov_b32_dpp v66, v15 quad_perm:[2,3,0,1] row_mask:0xf bank_mask:0xf
	s_waitcnt lgkmcnt(0)
	v_add_f32_e32 v64, v67, v65
	s_nop 0
	s_nop 1
	v_mov_b32_dpp v65, v64 quad_perm:[2,3,0,1] row_mask:0xf bank_mask:0xf
	s_and_saveexec_b64 s[2:3], vcc
	s_cbranch_execz .LBB0_1611
	s_cmpk_gt_u32 s4, 0x7f
	s_cbranch_scc1 .LBB0_1609
	s_waitcnt lgkmcnt(0)
	v_add_f32_e32 v15, v15, v66
	ds_add_f32 v12, v15 offset:48

.LBB0_1611:
	s_or_b64 exec, exec, s[2:3]
	v_exp_f32_e32 v15, v76
	s_waitcnt lgkmcnt(0)
	v_exp_f32_e32 v65, v77
	v_add_u32_e32 v64, 0x180, v13
	v_exp_f32_e32 v66, v78
	v_mul_f32_e32 v15, v190, v15
	v_cmp_le_i32_e64 s[0:1], v64, v188
	v_add_u32_e32 v64, 0x190, v13
	v_mul_f32_e32 v65, v190, v65
	v_cndmask_b32_e64 v15, 0, v15, s[0:1]
	v_cmp_le_i32_e64 s[0:1], v64, v188
	v_exp_f32_e32 v67, v79
	v_mul_f32_e32 v66, v190, v66
	v_cndmask_b32_e64 v64, 0, v65, s[0:1]
	v_add_u32_e32 v65, 0x1a0, v13
	v_cmp_le_i32_e64 s[0:1], v65, v188
	v_mul_f32_e32 v67, v190, v67
	v_add_f32_e32 v15, v15, v64
	v_cndmask_b32_e64 v65, 0, v66, s[0:1]
	v_add_u32_e32 v66, 0x1b0, v13
	v_cmp_le_i32_e64 s[0:1], v66, v188
	s_nop 1
	v_cndmask_b32_e64 v67, 0, v67, s[0:1]
	v_add_f32_e32 v64, v65, v67
	v_add_f32_e32 v15, v15, v64
	s_nop 1
	v_mov_b32_dpp v64, v15 quad_perm:[1,0,3,2] row_mask:0xf bank_mask:0xf
	s_waitcnt lgkmcnt(0)
	v_add_f32_e32 v15, v15, v64
	s_nop 0
	s_nop 1
	v_mov_b32_dpp v65, v67 quad_perm:[1,0,3,2] row_mask:0xf bank_mask:0xf
	s_nop 1
	v_mov_b32_dpp v66, v15 quad_perm:[2,3,0,1] row_mask:0xf bank_mask:0xf
	s_waitcnt lgkmcnt(0)
	v_add_f32_e32 v64, v67, v65
	s_nop 0
	s_nop 1
	v_mov_b32_dpp v65, v64 quad_perm:[2,3,0,1] row_mask:0xf bank_mask:0xf
	s_and_saveexec_b64 s[2:3], vcc
	s_cbranch_execz .LBB0_1573
	s_cmpk_gt_u32 s4, 0x7f
	s_cbranch_scc1 .LBB0_1614
	s_waitcnt lgkmcnt(0)
	v_add_f32_e32 v15, v15, v66
	ds_add_f32 v12, v15 offset:56
